# G1 and UP gemm epilogues: per-row rstd loads prefetched for the next unit at the end of the previous epilogue (spare VGPRs), epilogue uses v_mov instead of waiting on loads
# baseline (speedup 1.0000x reference)
; #define PG8_STAGE(bufoff, gbase, voff) do { _Pragma("unroll") for (int _i = 0; _i < 2; ++_i) \
;         __builtin_amdgcn_global_load_lds((const unsigned*)((const char*)(gbase) + (voff)[_i]), (PG8_LAS unsigned*)(lds + (bufoff) + ldsw + _i * 8192), 16, 0, 0); } while (0)
; #define PG8_WAIT_V(n) asm volatile("s_waitcnt vmcnt(" #n ")" ::: "memory")
; #define PG8_BAR __builtin_amdgcn_s_barrier()
;     __device__ __forceinline__ void operator()(const f32x4 (&acc)[2][2][4][2], const Unit& u, int wr, int wc, int fr, int fq) const {
;     ...
;         const int row0 = u.pm * BM + wr * 64 + fr, col0 = u.pn * BM + wc * 32 + 8 * fq;
;         float rsv[2][4];
;         if (RS) {
; #pragma unroll
;             for (int ai = 0; ai < 2; ++ai)
; #pragma unroll
;                 for (int m = 0; m < 4; ++m) rsv[ai][m] = rs[row0 + ai * HALF + m * 16];
; template <class Epi, class Sched, bool ALIGN_EPI = false, bool SP2 = false>
; __device__ __forceinline__ void gemm_phase(PG8_LAS unsigned char* lds, const Gemm g, const Sched& S, const Epi& E, const int tid_in) {
;     ...
;     const char* cA = (const char*)g.A + (size_t)cur.pm * tstepA; const char* cB = (const char*)g.Bt + (size_t)cur.pn * tstepB;
;     S.a_ready(cur);
;     if constexpr (SP2) {
;         PG8_STAGE(PG8_SB(0, 0), cB, voffB); PG8_STAGE(PG8_SB(0, 1), cB + hstepB, voffB); PG8_STAGE(PG8_SA(0, 0), cA, voffA); PG8_STAGE(PG8_SA(0, 1), cA + hstepA, voffA);
;         if (wr == 1) PG8_BAR;
;         PG8_WAIT_V(2); PG8_BAR;
;         PG8_STAGE(PG8_SB(1, 0), cB + kstep, voffB); PG8_STAGE(PG8_SA(1, 0), cA + kstep, voffA); PG8_STAGE(PG8_SB(1, 1), cB + hstepB + kstep, voffB);
;         PG8_WAIT_V(6); PG8_BAR;
;     } else {
;         PG8_STAGE(PG8_SB(0, 0), cB, voffB); PG8_STAGE(PG8_SA(0, 0), cA, voffA); PG8_STAGE(PG8_SB(0, 1), cB + hstepB, voffB); PG8_STAGE(PG8_SA(0, 1), cA + hstepA, voffA);
;         if (wr == 1) PG8_BAR;
;         PG8_WAIT_V(4); PG8_BAR;
;         PG8_STAGE(PG8_SB(1, 0), cB + kstep, voffB); PG8_STAGE(PG8_SA(1, 0), cA + kstep, voffA); PG8_STAGE(PG8_SB(1, 1), cB + hstepB + kstep, voffB);
;         PG8_WAIT_V(6); PG8_BAR;
.LBB0_280:
	s_add_u32 s2, s6, 0x9200000
	s_addc_u32 s3, s7, 0
	s_add_u32 s8, s6, 0x1f200000
	s_addc_u32 s9, s7, 0
	s_lshl_b32 s6, s11, 5
	s_and_b32 s36, s6, 0x60
	s_add_i32 m0, s29, 0x18000
	v_lshl_add_u64 v[6:7], v[6:7], 0, s[50:51]
	s_lshl_b32 s35, s12, 6
	s_lshl_b32 s12, s12, 13
	s_lshl_b32 s11, s36, 7
	s_waitcnt vmcnt(2)
	s_barrier
	global_load_lds_dwordx4 v[6:7], off
	v_lshl_add_u64 v[4:5], v[4:5], 0, s[50:51]
	s_add_i32 m0, s29, 0x1a000
	s_add_i32 s37, s29, 0x8000
	s_add_i32 s38, s29, 0xa000
	global_load_lds_dwordx4 v[4:5], off
	v_lshl_add_u64 v[0:1], v[0:1], 0, s[50:51]
	s_mov_b32 m0, s37
	s_add_u32 s6, s22, 0x40080
	global_load_lds_dwordx4 v[0:1], off
	v_lshl_add_u64 v[0:1], v[2:3], 0, s[50:51]
	s_mov_b32 m0, s38
	s_addc_u32 s7, s23, 0
	global_load_lds_dwordx4 v[0:1], off
	s_add_i32 m0, s29, 0x1c000
	v_lshl_add_u64 v[0:1], s[6:7], 0, v[134:135]
	global_load_lds_dwordx4 v[0:1], off
	v_lshl_add_u64 v[0:1], s[6:7], 0, v[96:97]
	s_add_i32 m0, s29, 0x1e000
	s_movk_i32 s6, 0x3c0
	global_load_lds_dwordx4 v[0:1], off
	v_and_b32_e32 v0, 48, v8
	v_lshlrev_b32_e32 v1, 6, v8
	v_and_or_b32 v0, v1, s6, v0
	v_lshlrev_b32_e32 v1, 2, v8
	v_and_b32_e32 v1, 32, v1
	v_bitop3_b32 v2, v0, s12, v1 bitop3:0xde
	v_bitop3_b32 v143, s11, v0, v1 bitop3:0xf6
	v_lshlrev_b32_e32 v0, 14, v13
	v_and_b32_e32 v0, 0xffff8000, v0
	v_lshl_add_u32 v0, v12, 11, v0
	v_and_b32_e32 v1, 1, v13
	v_lshl_or_b32 v0, v1, 6, v0
	v_lshl_add_u32 v138, v14, 1, v0
	v_lshlrev_b32_e32 v0, 14, v9
	v_and_b32_e32 v0, 0xffff8000, v0
	s_waitcnt vmcnt(6)
	v_lshl_add_u32 v0, v10, 11, v0
	v_and_b32_e32 v1, 1, v9
	s_cmpk_lt_u32 s10, 0x100
	v_lshl_or_b32 v0, v1, 6, v0
	v_readlane_b32 s6, v253, 13
	s_cselect_b64 s[10:11], -1, 0
	v_mov_b32_e32 v139, v98
	v_lshl_add_u32 v140, v11, 1, v0
	v_mov_b32_e32 v141, v98
	s_mov_b32 s39, 0
	v_add_u32_e32 v145, 0, v2
	v_readlane_b32 s40, v253, 12
	s_mov_b32 s41, s6
	s_lshl_b32 s100, s41, 8
	s_add_i32 s100, s100, s35
	v_mbcnt_lo_u32_b32 v224, -1, 0
	v_mbcnt_hi_u32_b32 v224, -1, v224
	v_and_or_b32 v224, v224, 15, s100
	v_ashrrev_i32_e32 v225, 31, v224
	v_lshl_add_u64 v[224:225], v[224:225], 2, s[8:9]
	global_load_dword v226, v[224:225], off
	global_load_dword v227, v[224:225], off offset:64
	global_load_dword v228, v[224:225], off offset:128
	global_load_dword v229, v[224:225], off offset:192
	global_load_dword v230, v[224:225], off offset:512
	global_load_dword v231, v[224:225], off offset:576
	global_load_dword v232, v[224:225], off offset:640
	global_load_dword v233, v[224:225], off offset:704
	s_barrier
	v_readlane_b32 s7, v253, 14
	s_branch .LBB0_283

; DI unsigned pk2(float a, float b) { f32x2 v = {a, b}; bf16x2_t r = __builtin_convertvector(v, bf16x2_t); return __builtin_bit_cast(unsigned, r); }
; DI float sigm(float x) { return __builtin_amdgcn_rcpf(1.f + __builtin_amdgcn_exp2f(-1.4426950408889634f * x)); }
;     __device__ __forceinline__ void operator()(const f32x4 (&acc)[2][2][4][2], const Unit& u, int wr, int wc, int fr, int fq) const {
;     ...
;         const int row0 = u.pm * BM + wr * 64 + fr, col0 = u.pn * BM + wc * 32 + 8 * fq;
;         float rsv[2][4];
;         if (RS) {
; #pragma unroll
;             for (int ai = 0; ai < 2; ++ai)
; #pragma unroll
;                 for (int m = 0; m < 4; ++m) rsv[ai][m] = rs[row0 + ai * HALF + m * 16];
;         }
; #pragma unroll
;         for (int ai = 0; ai < 2; ++ai)
; #pragma unroll
;             for (int m = 0; m < 4; ++m) { bf16_t* rowp = O + (size_t)(row0 + ai * HALF + m * 16) * ldc + col0;
; #pragma unroll
;                 for (int bj = 0; bj < 2; ++bj) { f32x4 v0 = acc[ai][bj][m][0], v1 = acc[ai][bj][m][1];
;                     if (RS) { v0 = v0 * rsv[ai][m]; v1 = v1 * rsv[ai][m]; }
;                     if (ACT == 1) {
; #pragma unroll
;                         for (int e = 0; e < 4; ++e) { v0[e] = sigm(v0[e]); v1[e] = sigm(v1[e]); } }
;                     u32x4 w; w.x = pk2(v0[0], v0[1]); w.y = pk2(v0[2], v0[3]); w.z = pk2(v1[0], v1[1]); w.w = pk2(v1[2], v1[3]);
;                     *(u32x4*)(rowp + bj * HALF) = w; } }
.LBB0_289:
	s_lshl_b32 s13, s41, 8
	s_add_i32 s13, s13, s35
	v_mbcnt_lo_u32_b32 v142, -1, 0
	v_mbcnt_hi_u32_b32 v142, -1, v142
	s_andn2_b64 vcc, exec, s[6:7]
	v_and_or_b32 v154, v142, 15, s13
	v_ashrrev_i32_e32 v155, 31, v154
	v_lshl_add_u64 v[148:149], v[154:155], 2, s[8:9]
	v_mov_b32_e32 v166, v226
	v_or_b32_e32 v164, 16, v154
	v_ashrrev_i32_e32 v165, 31, v164
	v_ashrrev_i32_e32 v142, 1, v142
	v_lshl_add_u64 v[146:147], v[164:165], 2, s[8:9]
	v_and_b32_e32 v159, -8, v142
	v_mov_b32_e32 v142, v233
	v_mov_b32_e32 v162, v227
	v_or_b32_e32 v160, 32, v154
	v_ashrrev_i32_e32 v161, 31, v160
	v_lshl_add_u64 v[146:147], v[160:161], 2, s[8:9]
	v_mov_b32_e32 v158, v228
	v_mov_b32_e32 v150, v230
	v_or_b32_e32 v156, 48, v154
	v_ashrrev_i32_e32 v157, 31, v156
	v_lshl_add_u64 v[146:147], v[156:157], 2, s[8:9]
	v_mov_b32_e32 v152, v229
	v_mov_b32_e32 v144, v232
	s_lshl_b32 s13, s40, 8
	v_mov_b32_e32 v146, v231
	s_or_b32 s13, s13, s36
	v_add_u32_e32 v168, s13, v159
	v_ashrrev_i32_e32 v169, 31, v168
	v_mov_b64_e32 v[148:149], s[2:3]
	v_add_u32_e32 v157, 0x80, v154
	v_add_u32_e32 v153, 0x90, v154
	v_add_u32_e32 v151, 0xa0, v154
	v_add_u32_e32 v147, 0xb0, v154
	v_mad_i64_i32 v[170:171], s[20:21], v154, s90, v[148:149]
	v_lshlrev_b64 v[154:155], 1, v[168:169]
	v_lshl_add_u64 v[168:169], v[170:171], 0, v[154:155]
	s_waitcnt vmcnt(0)
	v_pk_mul_f32 v[130:131], v[130:131], v[166:167] op_sel_hi:[1,0]
	v_pk_mul_f32 v[128:129], v[128:129], v[166:167] op_sel_hi:[1,0]
	v_pk_mul_f32 v[170:171], v[126:127], v[166:167] op_sel_hi:[1,0]
	v_pk_mul_f32 v[126:127], v[124:125], v[166:167] op_sel_hi:[1,0]
	v_cvt_pk_bf16_f32 v124, v128, v129
	v_cvt_pk_bf16_f32 v125, v130, v131
	v_cvt_pk_bf16_f32 v126, v126, v127
	v_cvt_pk_bf16_f32 v127, v170, v171
	global_store_dwordx4 v[168:169], v[124:127], off
	v_pk_mul_f32 v[122:123], v[122:123], v[166:167] op_sel_hi:[1,0]
	v_pk_mul_f32 v[120:121], v[120:121], v[166:167] op_sel_hi:[1,0]
	v_pk_mul_f32 v[124:125], v[118:119], v[166:167] op_sel_hi:[1,0]
	v_pk_mul_f32 v[118:119], v[116:117], v[166:167] op_sel_hi:[1,0]
	v_cvt_pk_bf16_f32 v116, v120, v121
	v_cvt_pk_bf16_f32 v117, v122, v123
	v_cvt_pk_bf16_f32 v118, v118, v119
	v_cvt_pk_bf16_f32 v119, v124, v125
	global_store_dwordx4 v[168:169], v[116:119], off offset:256
	v_pk_mul_f32 v[114:115], v[114:115], v[162:163] op_sel_hi:[1,0]
	v_pk_mul_f32 v[112:113], v[112:113], v[162:163] op_sel_hi:[1,0]
	v_mad_i64_i32 v[116:117], s[20:21], v164, s90, v[148:149]
	v_pk_mul_f32 v[118:119], v[110:111], v[162:163] op_sel_hi:[1,0]
	v_pk_mul_f32 v[110:111], v[108:109], v[162:163] op_sel_hi:[1,0]
	v_lshl_add_u64 v[116:117], v[116:117], 0, v[154:155]
	v_cvt_pk_bf16_f32 v108, v112, v113
	v_cvt_pk_bf16_f32 v109, v114, v115
	v_cvt_pk_bf16_f32 v110, v110, v111
	v_cvt_pk_bf16_f32 v111, v118, v119
	global_store_dwordx4 v[116:117], v[108:111], off
	v_pk_mul_f32 v[106:107], v[106:107], v[162:163] op_sel_hi:[1,0]
	v_pk_mul_f32 v[104:105], v[104:105], v[162:163] op_sel_hi:[1,0]
	v_pk_mul_f32 v[108:109], v[102:103], v[162:163] op_sel_hi:[1,0]
	v_pk_mul_f32 v[102:103], v[100:101], v[162:163] op_sel_hi:[1,0]
	v_cvt_pk_bf16_f32 v100, v104, v105
	v_cvt_pk_bf16_f32 v101, v106, v107
	v_cvt_pk_bf16_f32 v102, v102, v103
	v_cvt_pk_bf16_f32 v103, v108, v109
	global_store_dwordx4 v[116:117], v[100:103], off offset:256
	v_pk_mul_f32 v[94:95], v[94:95], v[158:159] op_sel_hi:[1,0]
	v_pk_mul_f32 v[92:93], v[92:93], v[158:159] op_sel_hi:[1,0]
	v_mad_i64_i32 v[100:101], s[20:21], v160, s90, v[148:149]
	v_pk_mul_f32 v[102:103], v[90:91], v[158:159] op_sel_hi:[1,0]
	v_pk_mul_f32 v[90:91], v[88:89], v[158:159] op_sel_hi:[1,0]
	v_lshl_add_u64 v[100:101], v[100:101], 0, v[154:155]
	v_cvt_pk_bf16_f32 v88, v92, v93
	v_cvt_pk_bf16_f32 v89, v94, v95
	v_cvt_pk_bf16_f32 v90, v90, v91
	v_cvt_pk_bf16_f32 v91, v102, v103
	global_store_dwordx4 v[100:101], v[88:91], off
	v_pk_mul_f32 v[82:83], v[82:83], v[158:159] op_sel_hi:[1,0]
	v_pk_mul_f32 v[80:81], v[80:81], v[158:159] op_sel_hi:[1,0]
	v_pk_mul_f32 v[88:89], v[74:75], v[158:159] op_sel_hi:[1,0]
	v_pk_mul_f32 v[74:75], v[72:73], v[158:159] op_sel_hi:[1,0]
	v_cvt_pk_bf16_f32 v72, v80, v81
	v_cvt_pk_bf16_f32 v73, v82, v83
	v_cvt_pk_bf16_f32 v74, v74, v75
	v_cvt_pk_bf16_f32 v75, v88, v89
	global_store_dwordx4 v[100:101], v[72:75], off offset:256
	v_pk_mul_f32 v[78:79], v[78:79], v[152:153] op_sel_hi:[1,0]
	v_pk_mul_f32 v[76:77], v[76:77], v[152:153] op_sel_hi:[1,0]
	v_mad_i64_i32 v[72:73], s[20:21], v156, s90, v[148:149]
	v_lshl_add_u64 v[80:81], v[72:73], 0, v[154:155]
	v_pk_mul_f32 v[74:75], v[86:87], v[152:153] op_sel_hi:[1,0]
	v_pk_mul_f32 v[72:73], v[84:85], v[152:153] op_sel_hi:[1,0]
	v_pk_mul_f32 v[70:71], v[70:71], v[152:153] op_sel_hi:[1,0]
	v_cvt_pk_bf16_f32 v72, v72, v73
	v_cvt_pk_bf16_f32 v73, v74, v75
	v_cvt_pk_bf16_f32 v74, v76, v77
	v_cvt_pk_bf16_f32 v75, v78, v79
	global_store_dwordx4 v[80:81], v[72:75], off
	v_pk_mul_f32 v[68:69], v[68:69], v[152:153] op_sel_hi:[1,0]
; DI unsigned pk2(float a, float b) { f32x2 v = {a, b}; bf16x2_t r = __builtin_convertvector(v, bf16x2_t); return __builtin_bit_cast(unsigned, r); }
; DI float sigm(float x) { return __builtin_amdgcn_rcpf(1.f + __builtin_amdgcn_exp2f(-1.4426950408889634f * x)); }
; #define PG8_BAR __builtin_amdgcn_s_barrier()
;     __device__ __forceinline__ void operator()(const f32x4 (&acc)[2][2][4][2], const Unit& u, int wr, int wc, int fr, int fq) const {
;     ...
;             for (int m = 0; m < 4; ++m) { bf16_t* rowp = O + (size_t)(row0 + ai * HALF + m * 16) * ldc + col0;
; #pragma unroll
;                 for (int bj = 0; bj < 2; ++bj) { f32x4 v0 = acc[ai][bj][m][0], v1 = acc[ai][bj][m][1];
;                     if (RS) { v0 = v0 * rsv[ai][m]; v1 = v1 * rsv[ai][m]; }
;                     if (ACT == 1) {
; #pragma unroll
;                         for (int e = 0; e < 4; ++e) { v0[e] = sigm(v0[e]); v1[e] = sigm(v1[e]); } }
;                     u32x4 w; w.x = pk2(v0[0], v0[1]); w.y = pk2(v0[2], v0[3]); w.z = pk2(v1[0], v1[1]); w.w = pk2(v1[2], v1[3]);
;                     *(u32x4*)(rowp + bj * HALF) = w; } }
; template <class Epi, class Sched, bool ALIGN_EPI = false, bool SP2 = false>
; __device__ __forceinline__ void gemm_phase(PG8_LAS unsigned char* lds, const Gemm g, const Sched& S, const Epi& E, const int tid_in) {
;     ...
;         if (!has_next) break;
; #pragma unroll
;         for (int a = 0; a < 2; ++a)
; #pragma unroll
;             for (int b = 0; b < 2; ++b)
; #pragma unroll
;                 for (int m = 0; m < 4; ++m)
; #pragma unroll
;                     for (int n = 0; n < 2; ++n) acc[a][b][m][n] = (f32x4){zf_, zf_, zf_, zf_};
;         cur = nxt; cA = nA; cB = nB; ++ui;
;         if constexpr (ALIGN_EPI) { if (wr == 1) PG8_BAR; }
;     }
	v_pk_mul_f32 v[62:63], v[62:63], v[150:151] op_sel_hi:[1,0]
	v_pk_mul_f32 v[72:73], v[66:67], v[152:153] op_sel_hi:[1,0]
	v_pk_mul_f32 v[66:67], v[64:65], v[152:153] op_sel_hi:[1,0]
	v_cvt_pk_bf16_f32 v64, v68, v69
	v_cvt_pk_bf16_f32 v65, v70, v71
	v_cvt_pk_bf16_f32 v66, v66, v67
	v_cvt_pk_bf16_f32 v67, v72, v73
	global_store_dwordx4 v[80:81], v[64:67], off offset:256
	v_pk_mul_f32 v[60:61], v[60:61], v[150:151] op_sel_hi:[1,0]
	v_pk_mul_f32 v[50:51], v[50:51], v[150:151] op_sel_hi:[1,0]
	v_mad_i64_i32 v[64:65], s[20:21], v157, s90, v[148:149]
	v_pk_mul_f32 v[66:67], v[58:59], v[150:151] op_sel_hi:[1,0]
	v_pk_mul_f32 v[58:59], v[56:57], v[150:151] op_sel_hi:[1,0]
	v_lshl_add_u64 v[64:65], v[64:65], 0, v[154:155]
	v_cvt_pk_bf16_f32 v56, v60, v61
	v_cvt_pk_bf16_f32 v57, v62, v63
	v_cvt_pk_bf16_f32 v58, v58, v59
	v_cvt_pk_bf16_f32 v59, v66, v67
	global_store_dwordx4 v[64:65], v[56:59], off
	v_pk_mul_f32 v[48:49], v[48:49], v[150:151] op_sel_hi:[1,0]
	v_pk_mul_f32 v[46:47], v[46:47], v[146:147] op_sel_hi:[1,0]
	v_pk_mul_f32 v[56:57], v[42:43], v[150:151] op_sel_hi:[1,0]
	v_pk_mul_f32 v[42:43], v[40:41], v[150:151] op_sel_hi:[1,0]
	v_cvt_pk_bf16_f32 v40, v48, v49
	v_cvt_pk_bf16_f32 v41, v50, v51
	v_cvt_pk_bf16_f32 v42, v42, v43
	v_cvt_pk_bf16_f32 v43, v56, v57
	global_store_dwordx4 v[64:65], v[40:43], off offset:256
	v_pk_mul_f32 v[44:45], v[44:45], v[146:147] op_sel_hi:[1,0]
	v_pk_mul_f32 v[34:35], v[34:35], v[146:147] op_sel_hi:[1,0]
	v_mad_i64_i32 v[40:41], s[20:21], v153, s90, v[148:149]
	v_lshl_add_u64 v[48:49], v[40:41], 0, v[154:155]
	v_pk_mul_f32 v[42:43], v[54:55], v[146:147] op_sel_hi:[1,0]
	v_pk_mul_f32 v[40:41], v[52:53], v[146:147] op_sel_hi:[1,0]
	v_pk_mul_f32 v[32:33], v[32:33], v[146:147] op_sel_hi:[1,0]
	v_cvt_pk_bf16_f32 v40, v40, v41
	v_cvt_pk_bf16_f32 v41, v42, v43
	v_cvt_pk_bf16_f32 v42, v44, v45
	v_cvt_pk_bf16_f32 v43, v46, v47
	global_store_dwordx4 v[48:49], v[40:43], off
	v_pk_mul_f32 v[30:31], v[30:31], v[144:145] op_sel_hi:[1,0]
	v_pk_mul_f32 v[28:29], v[28:29], v[144:145] op_sel_hi:[1,0]
	v_pk_mul_f32 v[40:41], v[26:27], v[146:147] op_sel_hi:[1,0]
	v_pk_mul_f32 v[26:27], v[24:25], v[146:147] op_sel_hi:[1,0]
	v_cvt_pk_bf16_f32 v24, v32, v33
	v_cvt_pk_bf16_f32 v25, v34, v35
	v_cvt_pk_bf16_f32 v26, v26, v27
	v_cvt_pk_bf16_f32 v27, v40, v41
	global_store_dwordx4 v[48:49], v[24:27], off offset:256
	v_pk_mul_f32 v[18:19], v[18:19], v[144:145] op_sel_hi:[1,0]
	v_pk_mul_f32 v[16:17], v[16:17], v[144:145] op_sel_hi:[1,0]
	v_mad_i64_i32 v[24:25], s[20:21], v151, s90, v[148:149]
	v_lshl_add_u64 v[32:33], v[24:25], 0, v[154:155]
	v_pk_mul_f32 v[26:27], v[38:39], v[144:145] op_sel_hi:[1,0]
	v_pk_mul_f32 v[24:25], v[36:37], v[144:145] op_sel_hi:[1,0]
	v_pk_mul_f32 v[14:15], v[14:15], v[142:143] op_sel_hi:[1,0]
	v_cvt_pk_bf16_f32 v24, v24, v25
	v_cvt_pk_bf16_f32 v25, v26, v27
	v_cvt_pk_bf16_f32 v26, v28, v29
	v_cvt_pk_bf16_f32 v27, v30, v31
	global_store_dwordx4 v[32:33], v[24:27], off
	v_pk_mul_f32 v[12:13], v[12:13], v[142:143] op_sel_hi:[1,0]
	v_pk_mul_f32 v[6:7], v[6:7], v[142:143] op_sel_hi:[1,0]
	v_pk_mul_f32 v[24:25], v[10:11], v[144:145] op_sel_hi:[1,0]
	v_pk_mul_f32 v[10:11], v[8:9], v[144:145] op_sel_hi:[1,0]
	v_cvt_pk_bf16_f32 v8, v16, v17
	v_cvt_pk_bf16_f32 v9, v18, v19
	v_cvt_pk_bf16_f32 v10, v10, v11
	v_cvt_pk_bf16_f32 v11, v24, v25
	global_store_dwordx4 v[32:33], v[8:11], off offset:256
	v_pk_mul_f32 v[4:5], v[4:5], v[142:143] op_sel_hi:[1,0]
	s_nop 0
	v_mad_i64_i32 v[8:9], s[20:21], v147, s90, v[148:149]
	v_lshl_add_u64 v[16:17], v[8:9], 0, v[154:155]
	v_pk_mul_f32 v[10:11], v[22:23], v[142:143] op_sel_hi:[1,0]
	v_pk_mul_f32 v[8:9], v[20:21], v[142:143] op_sel_hi:[1,0]
	s_mov_b64 s[20:21], -1
	v_cvt_pk_bf16_f32 v8, v8, v9
	v_cvt_pk_bf16_f32 v9, v10, v11
	v_cvt_pk_bf16_f32 v10, v12, v13
	v_cvt_pk_bf16_f32 v11, v14, v15
	global_store_dwordx4 v[16:17], v[8:11], off
	s_nop 1
	v_pk_mul_f32 v[8:9], v[2:3], v[142:143] op_sel_hi:[1,0]
	v_pk_mul_f32 v[2:3], v[0:1], v[142:143] op_sel_hi:[1,0]
	v_cvt_pk_bf16_f32 v0, v4, v5
	v_cvt_pk_bf16_f32 v1, v6, v7
	v_cvt_pk_bf16_f32 v2, v2, v3
	v_cvt_pk_bf16_f32 v3, v8, v9
	global_store_dwordx4 v[16:17], v[0:3], off offset:256
	s_cbranch_vccnz .LBB0_282
	s_lshl_b32 s100, s14, 8
	s_add_i32 s100, s100, s35
	v_mbcnt_lo_u32_b32 v224, -1, 0
	v_mbcnt_hi_u32_b32 v224, -1, v224
	v_and_or_b32 v224, v224, 15, s100
	v_ashrrev_i32_e32 v225, 31, v224
	v_lshl_add_u64 v[224:225], v[224:225], 2, s[8:9]
	global_load_dword v226, v[224:225], off
	global_load_dword v227, v[224:225], off offset:64
	global_load_dword v228, v[224:225], off offset:128
	global_load_dword v229, v[224:225], off offset:192
	global_load_dword v230, v[224:225], off offset:512
	global_load_dword v231, v[224:225], off offset:576
	global_load_dword v232, v[224:225], off offset:640
	global_load_dword v233, v[224:225], off offset:704
	s_andn2_b64 vcc, exec, s[0:1]
	s_cbranch_vccnz .LBB0_281
	s_barrier
	s_branch .LBB0_281

; #define PG8_STAGE(bufoff, gbase, voff) do { _Pragma("unroll") for (int _i = 0; _i < 2; ++_i) \
;         __builtin_amdgcn_global_load_lds((const unsigned*)((const char*)(gbase) + (voff)[_i]), (PG8_LAS unsigned*)(lds + (bufoff) + ldsw + _i * 8192), 16, 0, 0); } while (0)
; #define PG8_WAIT_V(n) asm volatile("s_waitcnt vmcnt(" #n ")" ::: "memory")
; #define PG8_BAR __builtin_amdgcn_s_barrier()
;     __device__ __forceinline__ void operator()(const f32x4 (&acc)[2][2][4][2], const Unit& u, int wr, int wc, int fr, int fq) const {
;     ...
;         const int row0 = u.pm * BM + wr * 64 + fr, col0 = u.pn * BM + wc * 32 + 8 * fq;
;         float rsv[2][4];
;         if (RS) {
; #pragma unroll
;             for (int ai = 0; ai < 2; ++ai)
; #pragma unroll
;                 for (int m = 0; m < 4; ++m) rsv[ai][m] = rs[row0 + ai * HALF + m * 16];
; template <class Epi, class Sched, bool ALIGN_EPI = false, bool SP2 = false>
; __device__ __forceinline__ void gemm_phase(PG8_LAS unsigned char* lds, const Gemm g, const Sched& S, const Epi& E, const int tid_in) {
;     ...
;     const char* cA = (const char*)g.A + (size_t)cur.pm * tstepA; const char* cB = (const char*)g.Bt + (size_t)cur.pn * tstepB;
;     S.a_ready(cur);
;     if constexpr (SP2) {
;         PG8_STAGE(PG8_SB(0, 0), cB, voffB); PG8_STAGE(PG8_SB(0, 1), cB + hstepB, voffB); PG8_STAGE(PG8_SA(0, 0), cA, voffA); PG8_STAGE(PG8_SA(0, 1), cA + hstepA, voffA);
;         if (wr == 1) PG8_BAR;
;         PG8_WAIT_V(2); PG8_BAR;
;         PG8_STAGE(PG8_SB(1, 0), cB + kstep, voffB); PG8_STAGE(PG8_SA(1, 0), cA + kstep, voffA); PG8_STAGE(PG8_SB(1, 1), cB + hstepB + kstep, voffB);
;         PG8_WAIT_V(6); PG8_BAR;
;     } else {
;         PG8_STAGE(PG8_SB(0, 0), cB, voffB); PG8_STAGE(PG8_SA(0, 0), cA, voffA); PG8_STAGE(PG8_SB(0, 1), cB + hstepB, voffB); PG8_STAGE(PG8_SA(0, 1), cA + hstepA, voffA);
;         if (wr == 1) PG8_BAR;
;         PG8_WAIT_V(4); PG8_BAR;
;         PG8_STAGE(PG8_SB(1, 0), cB + kstep, voffB); PG8_STAGE(PG8_SA(1, 0), cA + kstep, voffA); PG8_STAGE(PG8_SB(1, 1), cB + hstepB + kstep, voffB);
;         PG8_WAIT_V(6); PG8_BAR;
.LBB0_843:
	s_add_u32 s12, s8, 0x9200000
	s_addc_u32 s13, s9, 0
	s_lshl_b64 s[16:17], s[14:15], 2
	s_add_u32 s8, s8, s16
	s_addc_u32 s9, s9, s17
	s_add_u32 s16, s8, 0x1f200000
	s_addc_u32 s17, s9, 0
	v_and_b32_e32 v15, 48, v13
	v_lshlrev_b32_e32 v16, 6, v13
	s_movk_i32 s9, 0x3c0
	v_lshlrev_b32_e32 v13, 2, v13
	s_lshl_b32 s8, s20, 13
	v_and_or_b32 v15, v16, s9, v15
	v_and_b32_e32 v13, 32, v13
	v_bitop3_b32 v16, v15, s8, v13 bitop3:0xde
	s_lshl_b32 s8, s19, 5
	s_and_b32 s45, s8, 0x60
	s_add_i32 m0, s41, 0x18000
	v_lshl_add_u64 v[6:7], v[6:7], 0, s[50:51]
	s_lshl_b32 s15, s20, 6
	s_lshl_b32 s8, s45, 7
	s_waitcnt vmcnt(2)
	s_barrier
	global_load_lds_dwordx4 v[6:7], off
	v_lshl_add_u64 v[4:5], v[4:5], 0, s[50:51]
	s_add_i32 m0, s41, 0x1a000
	s_add_i32 s46, s41, 0x8000
	s_add_i32 s47, s41, 0xa000
	v_bitop3_b32 v143, s8, v15, v13 bitop3:0xf6
	global_load_lds_dwordx4 v[4:5], off
	v_lshl_add_u64 v[0:1], v[0:1], 0, s[50:51]
	s_mov_b32 m0, s46
	s_add_u32 s8, s30, 0x40080
	global_load_lds_dwordx4 v[0:1], off
	v_lshl_add_u64 v[0:1], v[2:3], 0, s[50:51]
	s_mov_b32 m0, s47
	s_addc_u32 s9, s31, 0
	global_load_lds_dwordx4 v[0:1], off
	s_add_i32 m0, s41, 0x1c000
	v_lshl_add_u64 v[0:1], s[8:9], 0, v[134:135]
	global_load_lds_dwordx4 v[0:1], off
	v_lshl_add_u64 v[0:1], s[8:9], 0, v[96:97]
	s_add_i32 m0, s41, 0x1e000
	s_cmpk_lt_u32 s18, 0x100
	global_load_lds_dwordx4 v[0:1], off
	v_lshlrev_b32_e32 v0, 14, v12
	v_and_b32_e32 v0, 0xffff8000, v0
	v_lshl_add_u32 v0, v11, 11, v0
	v_and_b32_e32 v1, 1, v12
	v_lshl_or_b32 v0, v1, 6, v0
	v_lshl_add_u32 v138, v14, 1, v0
	v_lshlrev_b32_e32 v0, 14, v8
	v_and_b32_e32 v0, 0xffff8000, v0
	s_waitcnt vmcnt(6)
	v_lshl_add_u32 v0, v9, 11, v0
	v_and_b32_e32 v1, 1, v8
	v_lshl_or_b32 v0, v1, 6, v0
	v_readlane_b32 s8, v253, 28
	s_cselect_b64 s[18:19], -1, 0
	v_mov_b32_e32 v139, v98
	v_lshl_add_u32 v140, v10, 1, v0
	v_mov_b32_e32 v141, v98
	s_mov_b32 s48, 0
	v_add_u32_e32 v145, 0, v16
	v_readlane_b32 s49, v253, 27
	s_mov_b32 s52, s8
	s_lshl_b32 s100, s52, 8
	s_add_i32 s100, s100, s15
	v_mbcnt_lo_u32_b32 v224, -1, 0
	v_mbcnt_hi_u32_b32 v224, -1, v224
	v_and_or_b32 v224, v224, 15, s100
	v_ashrrev_i32_e32 v225, 31, v224
	v_lshl_add_u64 v[224:225], v[224:225], 2, s[16:17]
	global_load_dword v226, v[224:225], off
	global_load_dword v227, v[224:225], off offset:64
	global_load_dword v228, v[224:225], off offset:128
	global_load_dword v229, v[224:225], off offset:192
	global_load_dword v230, v[224:225], off offset:512
	global_load_dword v231, v[224:225], off offset:576
	global_load_dword v232, v[224:225], off offset:640
	global_load_dword v233, v[224:225], off offset:704
	s_barrier
	v_readlane_b32 s9, v253, 29
	s_branch .LBB0_846

; DI unsigned pk2(float a, float b) { f32x2 v = {a, b}; bf16x2_t r = __builtin_convertvector(v, bf16x2_t); return __builtin_bit_cast(unsigned, r); }
; DI float sigm(float x) { return __builtin_amdgcn_rcpf(1.f + __builtin_amdgcn_exp2f(-1.4426950408889634f * x)); }
;     __device__ __forceinline__ void operator()(const f32x4 (&acc)[2][2][4][2], const Unit& u, int wr, int wc, int fr, int fq) const {
;     ...
;         const int row0 = u.pm * BM + wr * 64 + fr, col0 = u.pn * BM + wc * 32 + 8 * fq;
;         float rsv[2][4];
;         if (RS) {
; #pragma unroll
;             for (int ai = 0; ai < 2; ++ai)
; #pragma unroll
;                 for (int m = 0; m < 4; ++m) rsv[ai][m] = rs[row0 + ai * HALF + m * 16];
;         }
; #pragma unroll
;         for (int ai = 0; ai < 2; ++ai)
; #pragma unroll
;             for (int m = 0; m < 4; ++m) { bf16_t* rowp = O + (size_t)(row0 + ai * HALF + m * 16) * ldc + col0;
; #pragma unroll
;                 for (int bj = 0; bj < 2; ++bj) { f32x4 v0 = acc[ai][bj][m][0], v1 = acc[ai][bj][m][1];
;                     if (RS) { v0 = v0 * rsv[ai][m]; v1 = v1 * rsv[ai][m]; }
;                     if (ACT == 1) {
; #pragma unroll
;                         for (int e = 0; e < 4; ++e) { v0[e] = sigm(v0[e]); v1[e] = sigm(v1[e]); } }
;                     u32x4 w; w.x = pk2(v0[0], v0[1]); w.y = pk2(v0[2], v0[3]); w.z = pk2(v1[0], v1[1]); w.w = pk2(v1[2], v1[3]);
;                     *(u32x4*)(rowp + bj * HALF) = w; } }
.LBB0_852:
	s_lshl_b32 s21, s52, 8
	s_add_i32 s21, s21, s15
	v_mbcnt_lo_u32_b32 v142, -1, 0
	v_mbcnt_hi_u32_b32 v142, -1, v142
	s_andn2_b64 vcc, exec, s[8:9]
	v_and_or_b32 v152, v142, 15, s21
	v_ashrrev_i32_e32 v153, 31, v152
	v_lshl_add_u64 v[148:149], v[152:153], 2, s[16:17]
	v_mov_b32_e32 v160, v226
	v_mov_b32_e32 v158, v227
	v_mov_b32_e32 v156, v228
	v_mov_b32_e32 v154, v229
	v_mov_b32_e32 v150, v230
	v_mov_b32_e32 v146, v231
	v_mov_b32_e32 v144, v232
	v_ashrrev_i32_e32 v142, 1, v142
	v_and_b32_e32 v161, -8, v142
	v_mov_b32_e32 v142, v233
	s_lshl_b32 s21, s49, 8
	s_or_b32 s21, s21, s45
	v_add_u32_e32 v162, s21, v161
	v_ashrrev_i32_e32 v163, 31, v162
	v_mov_b64_e32 v[148:149], s[12:13]
	v_or_b32_e32 v166, 16, v152
	v_or_b32_e32 v167, 32, v152
	v_or_b32_e32 v159, 48, v152
	v_add_u32_e32 v157, 0x80, v152
	v_add_u32_e32 v155, 0x90, v152
	v_add_u32_e32 v151, 0xa0, v152
	v_add_u32_e32 v147, 0xb0, v152
	v_mad_i64_i32 v[164:165], s[28:29], v152, s72, v[148:149]
	v_lshlrev_b64 v[152:153], 1, v[162:163]
	v_lshl_add_u64 v[162:163], v[164:165], 0, v[152:153]
	s_waitcnt vmcnt(0)
	v_pk_mul_f32 v[130:131], v[130:131], v[160:161] op_sel_hi:[1,0]
	v_pk_mul_f32 v[128:129], v[128:129], v[160:161] op_sel_hi:[1,0]
	v_pk_mul_f32 v[164:165], v[126:127], v[160:161] op_sel_hi:[1,0]
	v_pk_mul_f32 v[126:127], v[124:125], v[160:161] op_sel_hi:[1,0]
	v_cvt_pk_bf16_f32 v124, v128, v129
	v_cvt_pk_bf16_f32 v125, v130, v131
	v_cvt_pk_bf16_f32 v126, v126, v127
	v_cvt_pk_bf16_f32 v127, v164, v165
	global_store_dwordx4 v[162:163], v[124:127], off
	v_pk_mul_f32 v[122:123], v[122:123], v[160:161] op_sel_hi:[1,0]
	v_pk_mul_f32 v[120:121], v[120:121], v[160:161] op_sel_hi:[1,0]
	v_pk_mul_f32 v[124:125], v[118:119], v[160:161] op_sel_hi:[1,0]
	v_pk_mul_f32 v[118:119], v[116:117], v[160:161] op_sel_hi:[1,0]
	v_cvt_pk_bf16_f32 v116, v120, v121
	v_cvt_pk_bf16_f32 v117, v122, v123
	v_cvt_pk_bf16_f32 v118, v118, v119
	v_cvt_pk_bf16_f32 v119, v124, v125
	global_store_dwordx4 v[162:163], v[116:119], off offset:256
	v_pk_mul_f32 v[114:115], v[114:115], v[158:159] op_sel_hi:[1,0]
	v_pk_mul_f32 v[112:113], v[112:113], v[158:159] op_sel_hi:[1,0]
	v_mad_i64_i32 v[116:117], s[28:29], v166, s72, v[148:149]
	v_pk_mul_f32 v[118:119], v[110:111], v[158:159] op_sel_hi:[1,0]
	v_pk_mul_f32 v[110:111], v[108:109], v[158:159] op_sel_hi:[1,0]
	v_lshl_add_u64 v[116:117], v[116:117], 0, v[152:153]
	v_cvt_pk_bf16_f32 v108, v112, v113
	v_cvt_pk_bf16_f32 v109, v114, v115
	v_cvt_pk_bf16_f32 v110, v110, v111
	v_cvt_pk_bf16_f32 v111, v118, v119
	global_store_dwordx4 v[116:117], v[108:111], off
	v_pk_mul_f32 v[106:107], v[106:107], v[158:159] op_sel_hi:[1,0]
	v_pk_mul_f32 v[104:105], v[104:105], v[158:159] op_sel_hi:[1,0]
	v_pk_mul_f32 v[108:109], v[102:103], v[158:159] op_sel_hi:[1,0]
	v_pk_mul_f32 v[102:103], v[100:101], v[158:159] op_sel_hi:[1,0]
	v_cvt_pk_bf16_f32 v100, v104, v105
	v_cvt_pk_bf16_f32 v101, v106, v107
	v_cvt_pk_bf16_f32 v102, v102, v103
	v_cvt_pk_bf16_f32 v103, v108, v109
	global_store_dwordx4 v[116:117], v[100:103], off offset:256
	v_pk_mul_f32 v[94:95], v[94:95], v[156:157] op_sel_hi:[1,0]
	v_pk_mul_f32 v[92:93], v[92:93], v[156:157] op_sel_hi:[1,0]
	v_mad_i64_i32 v[100:101], s[28:29], v167, s72, v[148:149]
	v_pk_mul_f32 v[102:103], v[90:91], v[156:157] op_sel_hi:[1,0]
	v_pk_mul_f32 v[90:91], v[88:89], v[156:157] op_sel_hi:[1,0]
	v_lshl_add_u64 v[100:101], v[100:101], 0, v[152:153]
	v_cvt_pk_bf16_f32 v88, v92, v93
	v_cvt_pk_bf16_f32 v89, v94, v95
	v_cvt_pk_bf16_f32 v90, v90, v91
	v_cvt_pk_bf16_f32 v91, v102, v103
	global_store_dwordx4 v[100:101], v[88:91], off
	v_pk_mul_f32 v[86:87], v[86:87], v[156:157] op_sel_hi:[1,0]
	v_pk_mul_f32 v[84:85], v[84:85], v[156:157] op_sel_hi:[1,0]
	v_pk_mul_f32 v[88:89], v[82:83], v[156:157] op_sel_hi:[1,0]
	v_pk_mul_f32 v[82:83], v[80:81], v[156:157] op_sel_hi:[1,0]
	v_cvt_pk_bf16_f32 v80, v84, v85
	v_cvt_pk_bf16_f32 v81, v86, v87
	v_cvt_pk_bf16_f32 v82, v82, v83
	v_cvt_pk_bf16_f32 v83, v88, v89
	global_store_dwordx4 v[100:101], v[80:83], off offset:256
	v_pk_mul_f32 v[78:79], v[78:79], v[154:155] op_sel_hi:[1,0]
	v_pk_mul_f32 v[76:77], v[76:77], v[154:155] op_sel_hi:[1,0]
	v_mad_i64_i32 v[80:81], s[28:29], v159, s72, v[148:149]
	v_pk_mul_f32 v[82:83], v[74:75], v[154:155] op_sel_hi:[1,0]
	v_pk_mul_f32 v[74:75], v[72:73], v[154:155] op_sel_hi:[1,0]
	v_lshl_add_u64 v[80:81], v[80:81], 0, v[152:153]
	v_cvt_pk_bf16_f32 v72, v76, v77
	v_cvt_pk_bf16_f32 v73, v78, v79
	v_cvt_pk_bf16_f32 v74, v74, v75
	v_cvt_pk_bf16_f32 v75, v82, v83
	global_store_dwordx4 v[80:81], v[72:75], off
	v_pk_mul_f32 v[70:71], v[70:71], v[154:155] op_sel_hi:[1,0]
	v_pk_mul_f32 v[68:69], v[68:69], v[154:155] op_sel_hi:[1,0]
	v_pk_mul_f32 v[72:73], v[66:67], v[154:155] op_sel_hi:[1,0]
	v_pk_mul_f32 v[66:67], v[64:65], v[154:155] op_sel_hi:[1,0]
; DI unsigned pk2(float a, float b) { f32x2 v = {a, b}; bf16x2_t r = __builtin_convertvector(v, bf16x2_t); return __builtin_bit_cast(unsigned, r); }
; DI float sigm(float x) { return __builtin_amdgcn_rcpf(1.f + __builtin_amdgcn_exp2f(-1.4426950408889634f * x)); }
; #define PG8_BAR __builtin_amdgcn_s_barrier()
;     __device__ __forceinline__ void operator()(const f32x4 (&acc)[2][2][4][2], const Unit& u, int wr, int wc, int fr, int fq) const {
;     ...
;             for (int m = 0; m < 4; ++m) { bf16_t* rowp = O + (size_t)(row0 + ai * HALF + m * 16) * ldc + col0;
; #pragma unroll
;                 for (int bj = 0; bj < 2; ++bj) { f32x4 v0 = acc[ai][bj][m][0], v1 = acc[ai][bj][m][1];
;                     if (RS) { v0 = v0 * rsv[ai][m]; v1 = v1 * rsv[ai][m]; }
;                     if (ACT == 1) {
; #pragma unroll
;                         for (int e = 0; e < 4; ++e) { v0[e] = sigm(v0[e]); v1[e] = sigm(v1[e]); } }
;                     u32x4 w; w.x = pk2(v0[0], v0[1]); w.y = pk2(v0[2], v0[3]); w.z = pk2(v1[0], v1[1]); w.w = pk2(v1[2], v1[3]);
;                     *(u32x4*)(rowp + bj * HALF) = w; } }
; template <class Epi, class Sched, bool ALIGN_EPI = false, bool SP2 = false>
; __device__ __forceinline__ void gemm_phase(PG8_LAS unsigned char* lds, const Gemm g, const Sched& S, const Epi& E, const int tid_in) {
;     ...
;         if (!has_next) break;
; #pragma unroll
;         for (int a = 0; a < 2; ++a)
; #pragma unroll
;             for (int b = 0; b < 2; ++b)
; #pragma unroll
;                 for (int m = 0; m < 4; ++m)
; #pragma unroll
;                     for (int n = 0; n < 2; ++n) acc[a][b][m][n] = (f32x4){zf_, zf_, zf_, zf_};
;         cur = nxt; cA = nA; cB = nB; ++ui;
;         if constexpr (ALIGN_EPI) { if (wr == 1) PG8_BAR; }
;     }
	v_cvt_pk_bf16_f32 v64, v68, v69
	v_cvt_pk_bf16_f32 v65, v70, v71
	v_cvt_pk_bf16_f32 v66, v66, v67
	v_cvt_pk_bf16_f32 v67, v72, v73
	global_store_dwordx4 v[80:81], v[64:67], off offset:256
	v_pk_mul_f32 v[62:63], v[62:63], v[150:151] op_sel_hi:[1,0]
	v_pk_mul_f32 v[60:61], v[60:61], v[150:151] op_sel_hi:[1,0]
	v_mad_i64_i32 v[64:65], s[28:29], v157, s72, v[148:149]
	v_pk_mul_f32 v[66:67], v[58:59], v[150:151] op_sel_hi:[1,0]
	v_pk_mul_f32 v[58:59], v[56:57], v[150:151] op_sel_hi:[1,0]
	v_lshl_add_u64 v[64:65], v[64:65], 0, v[152:153]
	v_cvt_pk_bf16_f32 v56, v60, v61
	v_cvt_pk_bf16_f32 v57, v62, v63
	v_cvt_pk_bf16_f32 v58, v58, v59
	v_cvt_pk_bf16_f32 v59, v66, v67
	global_store_dwordx4 v[64:65], v[56:59], off
	v_pk_mul_f32 v[50:51], v[50:51], v[150:151] op_sel_hi:[1,0]
	v_pk_mul_f32 v[48:49], v[48:49], v[150:151] op_sel_hi:[1,0]
	v_pk_mul_f32 v[56:57], v[42:43], v[150:151] op_sel_hi:[1,0]
	v_pk_mul_f32 v[42:43], v[40:41], v[150:151] op_sel_hi:[1,0]
	v_cvt_pk_bf16_f32 v40, v48, v49
	v_cvt_pk_bf16_f32 v41, v50, v51
	v_cvt_pk_bf16_f32 v42, v42, v43
	v_cvt_pk_bf16_f32 v43, v56, v57
	global_store_dwordx4 v[64:65], v[40:43], off offset:256
	v_pk_mul_f32 v[46:47], v[46:47], v[146:147] op_sel_hi:[1,0]
	v_pk_mul_f32 v[44:45], v[44:45], v[146:147] op_sel_hi:[1,0]
	v_mad_i64_i32 v[40:41], s[28:29], v155, s72, v[148:149]
	v_lshl_add_u64 v[48:49], v[40:41], 0, v[152:153]
	v_pk_mul_f32 v[42:43], v[54:55], v[146:147] op_sel_hi:[1,0]
	v_pk_mul_f32 v[40:41], v[52:53], v[146:147] op_sel_hi:[1,0]
	v_pk_mul_f32 v[34:35], v[34:35], v[146:147] op_sel_hi:[1,0]
	v_cvt_pk_bf16_f32 v40, v40, v41
	v_cvt_pk_bf16_f32 v41, v42, v43
	v_cvt_pk_bf16_f32 v42, v44, v45
	v_cvt_pk_bf16_f32 v43, v46, v47
	global_store_dwordx4 v[48:49], v[40:43], off
	v_pk_mul_f32 v[32:33], v[32:33], v[146:147] op_sel_hi:[1,0]
	v_pk_mul_f32 v[30:31], v[30:31], v[144:145] op_sel_hi:[1,0]
	v_pk_mul_f32 v[40:41], v[26:27], v[146:147] op_sel_hi:[1,0]
	v_pk_mul_f32 v[26:27], v[24:25], v[146:147] op_sel_hi:[1,0]
	v_cvt_pk_bf16_f32 v24, v32, v33
	v_cvt_pk_bf16_f32 v25, v34, v35
	v_cvt_pk_bf16_f32 v26, v26, v27
	v_cvt_pk_bf16_f32 v27, v40, v41
	global_store_dwordx4 v[48:49], v[24:27], off offset:256
	v_pk_mul_f32 v[28:29], v[28:29], v[144:145] op_sel_hi:[1,0]
	v_pk_mul_f32 v[18:19], v[18:19], v[144:145] op_sel_hi:[1,0]
	v_mad_i64_i32 v[24:25], s[28:29], v151, s72, v[148:149]
	v_lshl_add_u64 v[32:33], v[24:25], 0, v[152:153]
	v_pk_mul_f32 v[26:27], v[38:39], v[144:145] op_sel_hi:[1,0]
	v_pk_mul_f32 v[24:25], v[36:37], v[144:145] op_sel_hi:[1,0]
	v_pk_mul_f32 v[16:17], v[16:17], v[144:145] op_sel_hi:[1,0]
	v_cvt_pk_bf16_f32 v24, v24, v25
	v_cvt_pk_bf16_f32 v25, v26, v27
	v_cvt_pk_bf16_f32 v26, v28, v29
	v_cvt_pk_bf16_f32 v27, v30, v31
	global_store_dwordx4 v[32:33], v[24:27], off
	v_pk_mul_f32 v[14:15], v[14:15], v[142:143] op_sel_hi:[1,0]
	v_pk_mul_f32 v[12:13], v[12:13], v[142:143] op_sel_hi:[1,0]
	v_pk_mul_f32 v[24:25], v[10:11], v[144:145] op_sel_hi:[1,0]
	v_pk_mul_f32 v[10:11], v[8:9], v[144:145] op_sel_hi:[1,0]
	v_cvt_pk_bf16_f32 v8, v16, v17
	v_cvt_pk_bf16_f32 v9, v18, v19
	v_cvt_pk_bf16_f32 v10, v10, v11
	v_cvt_pk_bf16_f32 v11, v24, v25
	global_store_dwordx4 v[32:33], v[8:11], off offset:256
	v_pk_mul_f32 v[6:7], v[6:7], v[142:143] op_sel_hi:[1,0]
	v_pk_mul_f32 v[4:5], v[4:5], v[142:143] op_sel_hi:[1,0]
	v_mad_i64_i32 v[8:9], s[28:29], v147, s72, v[148:149]
	v_lshl_add_u64 v[16:17], v[8:9], 0, v[152:153]
	v_pk_mul_f32 v[10:11], v[22:23], v[142:143] op_sel_hi:[1,0]
	v_pk_mul_f32 v[8:9], v[20:21], v[142:143] op_sel_hi:[1,0]
	s_mov_b64 s[28:29], -1
	v_cvt_pk_bf16_f32 v8, v8, v9
	v_cvt_pk_bf16_f32 v9, v10, v11
	v_cvt_pk_bf16_f32 v10, v12, v13
	v_cvt_pk_bf16_f32 v11, v14, v15
	global_store_dwordx4 v[16:17], v[8:11], off
	s_nop 1
	v_pk_mul_f32 v[8:9], v[2:3], v[142:143] op_sel_hi:[1,0]
	v_pk_mul_f32 v[2:3], v[0:1], v[142:143] op_sel_hi:[1,0]
	v_cvt_pk_bf16_f32 v0, v4, v5
	v_cvt_pk_bf16_f32 v1, v6, v7
	v_cvt_pk_bf16_f32 v2, v2, v3
	v_cvt_pk_bf16_f32 v3, v8, v9
	global_store_dwordx4 v[16:17], v[0:3], off offset:256
	s_cbranch_vccnz .LBB0_845
	s_lshl_b32 s100, s22, 8
	s_add_i32 s100, s100, s15
	v_mbcnt_lo_u32_b32 v224, -1, 0
	v_mbcnt_hi_u32_b32 v224, -1, v224
	v_and_or_b32 v224, v224, 15, s100
	v_ashrrev_i32_e32 v225, 31, v224
	v_lshl_add_u64 v[224:225], v[224:225], 2, s[16:17]
	global_load_dword v226, v[224:225], off
	global_load_dword v227, v[224:225], off offset:64
	global_load_dword v228, v[224:225], off offset:128
	global_load_dword v229, v[224:225], off offset:192
	global_load_dword v230, v[224:225], off offset:512
	global_load_dword v231, v[224:225], off offset:576
	global_load_dword v232, v[224:225], off offset:640
	global_load_dword v233, v[224:225], off offset:704
	s_andn2_b64 vcc, exec, s[2:3]
	s_cbranch_vccnz .LBB0_844
	s_barrier
	s_branch .LBB0_844

; __global__ void __launch_bounds__(NTHR, 2) hybrid_fwd(Args a_unused) {
	.amdhsa_kernel _Z10hybrid_fwd4Args
		.amdhsa_group_segment_fixed_size 0
		.amdhsa_private_segment_fixed_size 0
		.amdhsa_kernarg_size 464
		.amdhsa_user_sgpr_count 2
		.amdhsa_user_sgpr_dispatch_ptr 0
		.amdhsa_user_sgpr_queue_ptr 0
		.amdhsa_user_sgpr_kernarg_segment_ptr 1
		.amdhsa_user_sgpr_dispatch_id 0
		.amdhsa_user_sgpr_kernarg_preload_length 0
		.amdhsa_user_sgpr_kernarg_preload_offset 0
		.amdhsa_user_sgpr_private_segment_size 0
		.amdhsa_uses_dynamic_stack 0
		.amdhsa_enable_private_segment 0
		.amdhsa_system_sgpr_workgroup_id_x 1
		.amdhsa_system_sgpr_workgroup_id_y 0
		.amdhsa_system_sgpr_workgroup_id_z 0
		.amdhsa_system_sgpr_workgroup_info 0
		.amdhsa_system_vgpr_workitem_id 2
		.amdhsa_next_free_vgpr 256
		.amdhsa_next_free_sgpr 102
		.amdhsa_accum_offset 256
		.amdhsa_reserve_vcc 1
		.amdhsa_float_round_mode_32 0
		.amdhsa_float_round_mode_16_64 0
		.amdhsa_float_denorm_mode_32 3
		.amdhsa_float_denorm_mode_16_64 3
		.amdhsa_dx10_clamp 1
		.amdhsa_ieee_mode 1
		.amdhsa_fp16_overflow 0
		.amdhsa_tg_split 0
		.amdhsa_exception_fp_ieee_invalid_op 0
		.amdhsa_exception_fp_denorm_src 0
		.amdhsa_exception_fp_ieee_div_zero 0
		.amdhsa_exception_fp_ieee_overflow 0
		.amdhsa_exception_fp_ieee_underflow 0
		.amdhsa_exception_fp_ieee_inexact 0
		.amdhsa_exception_int_div_zero 0
	.end_amdhsa_kernel

; __global__ void __launch_bounds__(NTHR, 2) hybrid_fwd(Args a_unused) {
;     extern __shared__ __attribute__((aligned(16))) unsigned char lds_raw[];
amdhsa.kernels:
  - .agpr_count:     0
    .args:
      - .offset:         0
        .size:           208
        .value_kind:     by_value
      - .offset:         208
        .size:           4
        .value_kind:     hidden_block_count_x
      - .offset:         212
        .size:           4
        .value_kind:     hidden_block_count_y
      - .offset:         216
        .size:           4
        .value_kind:     hidden_block_count_z
      - .offset:         220
        .size:           2
        .value_kind:     hidden_group_size_x
      - .offset:         222
        .size:           2
        .value_kind:     hidden_group_size_y
      - .offset:         224
        .size:           2
        .value_kind:     hidden_group_size_z
      - .offset:         226
        .size:           2
        .value_kind:     hidden_remainder_x
      - .offset:         228
        .size:           2
        .value_kind:     hidden_remainder_y
      - .offset:         230
        .size:           2
        .value_kind:     hidden_remainder_z
      - .offset:         248
        .size:           8
        .value_kind:     hidden_global_offset_x
      - .offset:         256
        .size:           8
        .value_kind:     hidden_global_offset_y
      - .offset:         264
        .size:           8
        .value_kind:     hidden_global_offset_z
      - .offset:         272
        .size:           2
        .value_kind:     hidden_grid_dims
      - .offset:         296
        .size:           8
        .value_kind:     hidden_multigrid_sync_arg
      - .offset:         328
        .size:           4
        .value_kind:     hidden_dynamic_lds_size
    .group_segment_fixed_size: 0
    .kernarg_segment_align: 8
    .kernarg_segment_size: 464
    .language:       OpenCL C
    .language_version:
      - 2
      - 0
    .max_flat_workgroup_size: 512
    .name:           _Z10hybrid_fwd4Args
    .private_segment_fixed_size: 0
    .sgpr_count:     108
    .sgpr_spill_count: 162
    .symbol:         _Z10hybrid_fwd4Args.kd
    .uniform_work_group_size: 1
    .uses_dynamic_stack: false
    .vgpr_count:     256
    .vgpr_spill_count: 0
    .wavefront_size: 64
